# v17 plus back-edge rotation of the diff-attn slot loop: counters / exit test / loop-carried moves issued before the slot barrier
# baseline (speedup 1.0000x reference)
; #define AB_DMAK(t, b) do { const char* _gb = (const char*)K + (size_t)(64 * (t)) * 128 * 2; _Pragma("unroll") for (int _j = 0; _j < 2; ++_j) \
;         __builtin_amdgcn_global_load_lds((const unsigned*)(_gb + kgoff[_j]), (LAS unsigned*)(lds + (b) * KBB + (2 * wid + _j) * 1024), 16, 0, 0); } while (0)
; #define AB_DMAV(t, b) do { const char* _gb = (const char*)V + (size_t)(64 * (t)) * 128 * 2; _Pragma("unroll") for (int _j = 0; _j < 4; ++_j) \
;         __builtin_amdgcn_global_load_lds((const unsigned*)(_gb + vgoff[_j]), (LAS unsigned*)(lds + VOFF + (b) * VBB + (4 * wid + _j) * 1024), 16, 0, 0); } while (0)
; #define AB_BAR() asm volatile("s_waitcnt vmcnt(0) lgkmcnt(0)\n\ts_barrier" ::: "memory")
; __device__ __forceinline__ void attn_b_unit(LAS unsigned char* lds, const bf16_t* __restrict__ Q, const bf16_t* __restrict__ K, const bf16_t* __restrict__ V, bf16_t* __restrict__ O, int q0) {
;     ...
;     for (int s = 0; s <= NT; ++s) {
;         if (s + 1 < NT) AB_DMAK(s + 1, (s + 1) & 1);
;         if (s < NT) AB_DMAV(s, s & 1);
;     ...
;         AB_BAR();
;     }
.LBB0_271:
	s_add_u32 s70, s70, 0x4000
	s_addc_u32 s71, s71, 0
	s_add_i32 s24, s24, 0x8000
	s_add_i32 s25, s25, 64
	s_waitcnt vmcnt(0) lgkmcnt(0)
	s_cmp_eq_u32 s48, s70
	s_cbranch_scc1 .Lslot_exit
	v_mov_b32_e32 v67, v0
	s_mov_b32 s21, s20
	s_add_i32 s20, s21, 1
	s_cmp_ge_u32 s20, s28
	s_barrier
	s_cbranch_scc0 .LBB0_257
	s_branch .LBB0_258
.Lslot_exit:
	s_barrier
